# static priority raise for waves 0-3 (the other half) at each GEMM unit-loop head, per-segment toggles removed
# speedup vs baseline: 1.0118x; 1.0118x over previous
; #define PG8_STAGE(bufoff, gbase, voff) do { _Pragma("unroll") for (int _i = 0; _i < 2; ++_i) \
;         __builtin_amdgcn_global_load_lds((const unsigned*)((const char*)(gbase) + (voff)[_i]), (LAS unsigned*)(lds + (bufoff) + ldsw + _i * 8192), 16, 0, 0); } while (0)
; #define PG8_LDA(dst, b, h) do { _Pragma("unroll") for (int m = 0; m < 4; ++m) _Pragma("unroll") for (int k = 0; k < 2; ++k) dst[m][k] = *(const LAS bf16x8*)(lds + PG8_SA(b, h) + aoff + m * 2048 + k * 1024); } while (0)
; #define PG8_LDB(dst, b, h) do { _Pragma("unroll") for (int n = 0; n < 2; ++n) _Pragma("unroll") for (int k = 0; k < 2; ++k) dst[n][k] = *(const LAS bf16x8*)(lds + PG8_SB(b, h) + boff + n * 2048 + k * 1024); } while (0)
; #define PG8_MMA(ai, bj, At, Bt) do { __builtin_amdgcn_s_setprio(1); _Pragma("unroll") for (int m = 0; m < 4; ++m) _Pragma("unroll") for (int n = 0; n < 2; ++n) _Pragma("unroll") for (int k = 0; k < 2; ++k) \
;         acc[ai][bj][m][n] = __builtin_amdgcn_mfma_f32_16x16x32_bf16(Bt[n][k], At[m][k], acc[ai][bj][m][n], 0, 0, 0); __builtin_amdgcn_s_setprio(0); } while (0)
; #define PG8_WAIT_V(n) asm volatile("s_waitcnt vmcnt(" #n ")" ::: "memory")
; #define PG8_WAIT_L(n) asm volatile("s_waitcnt lgkmcnt(" #n ")" ::: "memory")
; #define PG8_BAR __builtin_amdgcn_s_barrier()
; #define PG8_SCHED __builtin_amdgcn_sched_barrier(0)
; template <class Epi>
; __device__ __forceinline__ void gemm_phase(LAS unsigned char* lds, const Gemm g, const int G, const int cidx, const Epi& E) {
;     ...
;     for (;;) {
;         const bool has_next = S.next(ui + 1, nxt);
;         const char* nA = has_next ? PG8_ABASE(nxt) : cA; const char* nB = has_next ? (const char*)g.Bt + (size_t)nxt.pn * tstep : cB;
;         for (int t = 0; t < nt; t += 2) {
;             const bool last = (t == nt - 2);
;             const char* a1 = cA + (size_t)(t + 1) * kstep;
;             const char* a2 = last ? nA : cA + (size_t)(t + 2) * kstep; const char* b2 = last ? nB : cB + (size_t)(t + 2) * kstep;
;             const char* a3 = a2 + kstep; const char* b3 = b2 + kstep;
;             PG8_LDB(B0, 0, 0); PG8_LDB(B1, 0, 1); PG8_SCHED; PG8_LDA(At, 0, 0); PG8_STAGE(PG8_SA(1, 1), a1 + hstep, voffA);
;             PG8_WAIT_V(8); PG8_WAIT_L(0); PG8_BAR; PG8_MMA(0, 0, At, B0); PG8_MMA(0, 1, At, B1); PG8_BAR; PG8_SCHED;
.LBB0_79:
	v_readfirstlane_b32 s98, v202
	s_cmp_lt_u32 s98, 0x100
	s_cbranch_scc0 .Lgprio_c
	s_setprio 1
